# attention loop: cost-weighted spread of the 116 fillers over the 24 MFMA gaps (transcendental = 2x a plain VALU op)
# speedup vs baseline: 1.0065x; 1.0065x over previous
; #define SBAR() __builtin_amdgcn_sched_barrier(0)
; #define PK4(P, BASE, OUT) do { u32x4 w = {cvtpk(P[BASE + 0], P[BASE + 1]), cvtpk(P[BASE + 2], P[BASE + 3]), cvtpk(P[BASE + 4], P[BASE + 5]), cvtpk(P[BASE + 6], P[BASE + 7])}; \
;     OUT = *reinterpret_cast<bf16x8*>(&w); } while (0)
; template <int KS> __device__ __forceinline__ void pv_ks(f32x16* o, int vb, bf16x8 pa) {
;     const s16x4 l0 = tr_read<v_rd_off(0, KS, 0)>(vb), h0 = tr_read<v_rd_off(0, KS, 1)>(vb), l1 = tr_read<v_rd_off(1, KS, 0)>(vb), h1 = tr_read<v_rd_off(1, KS, 1)>(vb);
;     const s16x4 l2 = tr_read<v_rd_off(2, KS, 0)>(vb), h2 = tr_read<v_rd_off(2, KS, 1)>(vb), l3 = tr_read<v_rd_off(3, KS, 0)>(vb), h3 = tr_read<v_rd_off(3, KS, 1)>(vb);
;     ...
;     asm volatile("s_waitcnt lgkmcnt(6)" ::: "memory"); SBAR();
;     o[0] = __builtin_amdgcn_mfma_f32_32x32x16_bf16(pa, PK(l0, h0), o[0], 0, 0, 0);
;     asm volatile("s_waitcnt lgkmcnt(4)" ::: "memory"); SBAR();
;     o[1] = __builtin_amdgcn_mfma_f32_32x32x16_bf16(pa, PK(l1, h1), o[1], 0, 0, 0);
;     asm volatile("s_waitcnt lgkmcnt(2)" ::: "memory"); SBAR();
;     o[2] = __builtin_amdgcn_mfma_f32_32x32x16_bf16(pa, PK(l2, h2), o[2], 0, 0, 0);
;     asm volatile("s_waitcnt lgkmcnt(0)" ::: "memory"); SBAR();
;     o[3] = __builtin_amdgcn_mfma_f32_32x32x16_bf16(pa, PK(l3, h3), o[3], 0, 0, 0);
;     ...
; }
; __device__ __forceinline__ void pv_d0(f32x16* o, int vb, bf16x8 pa0, bf16x8 pa1, bf16x8 pa2, bf16x8 pa3) {
;     __builtin_amdgcn_s_setprio(1);
;     pv_ks<0>(o, vb, pa0); pv_ks<1>(o, vb, pa1); pv_ks<2>(o, vb, pa2); pv_ks<3>(o, vb, pa3);
;     __builtin_amdgcn_s_setprio(0);
; }
; __device__ __forceinline__ void exp_half(f32x16& p) {
; #pragma unroll
;     for (int r = 0; r < 16; ++r) p[r] = __builtin_amdgcn_exp2f(p[r]);
; }
; __device__ __forceinline__ void pack_p(const f32x16& p0, const f32x16& p1, float& l_reg, bf16x8& pa0, bf16x8& pa1, bf16x8& pa2, bf16x8& pa3) {
;     float ps = 0;
; #pragma unroll
;     for (int r = 0; r < 16; ++r) ps += p0[r];
; #pragma unroll
;     for (int r = 0; r < 16; ++r) ps += p1[r];
;     l_reg += ps;
;     ...
;     PK4(p0, 0, pa0); PK4(p0, 8, pa1); PK4(p1, 0, pa2); PK4(p1, 8, pa3);
;     ...
; }
.Lsym_nostage_s0:
	s_waitcnt lgkmcnt(14)
	v_mfma_f32_32x32x16_bf16 v[48:63], v[128:131], v[144:147], v[48:63]
	ds_read_b64_tr_b16 v[144:145], v252 offset:4096
	ds_read_b64_tr_b16 v[146:147], v252 offset:6144
	v_exp_f32_e32 v88, v88
	v_exp_f32_e32 v89, v89
	v_exp_f32_e32 v90, v90
	s_waitcnt lgkmcnt(9)
	v_mfma_f32_32x32x16_bf16 v[112:127], v[192:195], v[172:175], v[112:127]
	v_exp_f32_e32 v91, v91
	v_add_f32_e32 v182, v88, v182
	v_add_f32_e32 v182, v89, v182
	v_cvt_pk_bf16_f32 v132, v88, v89
	v_exp_f32_e32 v92, v92
	v_mfma_f32_32x32x16_bf16 v[32:47], v[128:131], v[148:151], v[32:47]
	ds_read_b64_tr_b16 v[148:149], v252 offset:4608
	ds_read_b64_tr_b16 v[150:151], v252 offset:6656
	v_exp_f32_e32 v93, v93
	v_add_f32_e32 v182, v90, v182
	v_add_f32_e32 v182, v91, v182
	v_cvt_pk_bf16_f32 v133, v90, v91
	s_waitcnt lgkmcnt(10)
	v_mfma_f32_32x32x16_bf16 v[96:111], v[196:199], v[172:175], v[96:111]
	v_exp_f32_e32 v94, v94
	v_exp_f32_e32 v95, v95
	v_add_f32_e32 v182, v92, v182
	v_add_f32_e32 v182, v93, v182
	v_mfma_f32_32x32x16_bf16 v[16:31], v[128:131], v[152:155], v[16:31]
	ds_read_b64_tr_b16 v[152:153], v252 offset:5120
	ds_read_b64_tr_b16 v[154:155], v252 offset:7168
	v_cvt_pk_bf16_f32 v134, v92, v93
	v_cvt_pk_bf16_f32 v135, v94, v95
	v_add_f32_e32 v182, v94, v182
	v_add_f32_e32 v182, v95, v182
	v_exp_f32_e32 v64, v64
	s_waitcnt lgkmcnt(11)
	v_mfma_f32_32x32x16_bf16 v[112:127], v[200:203], v[168:171], v[112:127]
	v_exp_f32_e32 v65, v65
	v_exp_f32_e32 v66, v66
	v_exp_f32_e32 v67, v67
	v_add_f32_e32 v182, v64, v182
	v_mfma_f32_32x32x16_bf16 v[0:15], v[128:131], v[156:159], v[0:15]
	ds_read_b64_tr_b16 v[156:157], v252 offset:5632
	ds_read_b64_tr_b16 v[158:159], v252 offset:7680
	v_add_f32_e32 v182, v65, v182
	v_cvt_pk_bf16_f32 v136, v64, v65
	v_exp_f32_e32 v68, v68
	v_exp_f32_e32 v69, v69
	s_waitcnt lgkmcnt(12)
	v_mfma_f32_32x32x16_bf16 v[96:111], v[204:207], v[168:171], v[96:111]
	v_add_f32_e32 v182, v66, v182
	v_add_f32_e32 v182, v67, v182
	v_cvt_pk_bf16_f32 v137, v66, v67
	v_exp_f32_e32 v70, v70
	s_waitcnt lgkmcnt(6)
	v_mfma_f32_32x32x16_bf16 v[48:63], v[132:135], v[144:147], v[48:63]
	ds_read_b64_tr_b16 v[144:145], v252 offset:8192
	ds_read_b64_tr_b16 v[146:147], v252 offset:10240
	v_exp_f32_e32 v71, v71
	v_add_f32_e32 v182, v68, v182
	v_add_f32_e32 v182, v69, v182
	v_cvt_pk_bf16_f32 v138, v68, v69
	v_cvt_pk_bf16_f32 v139, v70, v71
	v_add_f32_e32 v182, v70, v182
	v_mfma_f32_32x32x16_bf16 v[112:127], v[208:211], v[164:167], v[112:127]
	v_add_f32_e32 v182, v71, v182
	v_exp_f32_e32 v72, v72
	v_exp_f32_e32 v73, v73
	v_exp_f32_e32 v74, v74
	s_waitcnt lgkmcnt(6)
	v_mfma_f32_32x32x16_bf16 v[32:47], v[132:135], v[148:151], v[32:47]
	ds_read_b64_tr_b16 v[148:149], v252 offset:8704
	ds_read_b64_tr_b16 v[150:151], v252 offset:10752
	v_exp_f32_e32 v75, v75
	v_add_f32_e32 v182, v72, v182
	v_add_f32_e32 v182, v73, v182
	v_cvt_pk_bf16_f32 v140, v72, v73
	v_mfma_f32_32x32x16_bf16 v[96:111], v[212:215], v[164:167], v[96:111]
	v_exp_f32_e32 v76, v76
	v_exp_f32_e32 v77, v77
	v_add_f32_e32 v182, v74, v182
	v_add_f32_e32 v182, v75, v182
	s_waitcnt lgkmcnt(6)
	v_mfma_f32_32x32x16_bf16 v[16:31], v[132:135], v[152:155], v[16:31]
	ds_read_b64_tr_b16 v[152:153], v252 offset:9216
	ds_read_b64_tr_b16 v[154:155], v252 offset:11264
	v_cvt_pk_bf16_f32 v141, v74, v75
	v_exp_f32_e32 v78, v78
	v_exp_f32_e32 v79, v79
	v_add_f32_e32 v182, v76, v182
	v_mfma_f32_32x32x16_bf16 v[112:127], v[216:219], v[160:163], v[112:127]
	v_add_f32_e32 v182, v77, v182
	v_cvt_pk_bf16_f32 v142, v76, v77
	v_cvt_pk_bf16_f32 v143, v78, v79
	v_add_f32_e32 v182, v78, v182
	v_add_f32_e32 v182, v79, v182
	s_cmp_lt_i32 s55, 0
	s_cselect_b32 s100, -1.0, 1.0
	v_mul_f32_e32 v185, s100, v186
	s_waitcnt lgkmcnt(6)
	v_mfma_f32_32x32x16_bf16 v[0:15], v[132:135], v[156:159], v[0:15]
	ds_read_b64_tr_b16 v[156:157], v252 offset:9728
	ds_read_b64_tr_b16 v[158:159], v252 offset:11776
	v_fma_f32 v187, -v185, v183, s16
	v_fmamk_f32 v80, v185, 0x00000000, v187
	v_fmamk_f32 v81, v185, 0x3f800000, v187
	v_fmamk_f32 v82, v185, 0x40000000, v187
	v_fmamk_f32 v83, v185, 0x40400000, v187
	v_fmamk_f32 v84, v185, 0x41000000, v187
	v_mfma_f32_32x32x16_bf16 v[96:111], v[220:223], v[160:163], v[96:111]
	v_fmamk_f32 v85, v185, 0x41100000, v187
	v_fmamk_f32 v86, v185, 0x41200000, v187
	v_fmamk_f32 v87, v185, 0x41300000, v187
	v_fmamk_f32 v88, v185, 0x41800000, v187
	v_fmamk_f32 v89, v185, 0x41880000, v187
	v_fmamk_f32 v90, v185, 0x41900000, v187
	s_waitcnt lgkmcnt(6)
	v_mfma_f32_32x32x16_bf16 v[48:63], v[136:139], v[144:147], v[48:63]
	ds_read_b64_tr_b16 v[144:145], v252 offset:12288
	ds_read_b64_tr_b16 v[146:147], v252 offset:14336
	v_fmamk_f32 v91, v185, 0x41980000, v187
	v_fmamk_f32 v92, v185, 0x41c00000, v187
	v_fmamk_f32 v93, v185, 0x41c80000, v187
	v_fmamk_f32 v94, v185, 0x41d00000, v187
	v_fmamk_f32 v95, v185, 0x41d80000, v187
	v_fmamk_f32 v64, v185, 0x42000000, v187
	s_waitcnt lgkmcnt(6)
; #define SBAR() __builtin_amdgcn_sched_barrier(0)
; template <int KS> __device__ __forceinline__ void pv_ks(f32x16* o, int vb, bf16x8 pa) {
;     const s16x4 l0 = tr_read<v_rd_off(0, KS, 0)>(vb), h0 = tr_read<v_rd_off(0, KS, 1)>(vb), l1 = tr_read<v_rd_off(1, KS, 0)>(vb), h1 = tr_read<v_rd_off(1, KS, 1)>(vb);
;     const s16x4 l2 = tr_read<v_rd_off(2, KS, 0)>(vb), h2 = tr_read<v_rd_off(2, KS, 1)>(vb), l3 = tr_read<v_rd_off(3, KS, 0)>(vb), h3 = tr_read<v_rd_off(3, KS, 1)>(vb);
;     ...
;     asm volatile("s_waitcnt lgkmcnt(6)" ::: "memory"); SBAR();
;     o[0] = __builtin_amdgcn_mfma_f32_32x32x16_bf16(pa, PK(l0, h0), o[0], 0, 0, 0);
;     asm volatile("s_waitcnt lgkmcnt(4)" ::: "memory"); SBAR();
;     o[1] = __builtin_amdgcn_mfma_f32_32x32x16_bf16(pa, PK(l1, h1), o[1], 0, 0, 0);
;     asm volatile("s_waitcnt lgkmcnt(2)" ::: "memory"); SBAR();
;     o[2] = __builtin_amdgcn_mfma_f32_32x32x16_bf16(pa, PK(l2, h2), o[2], 0, 0, 0);
;     asm volatile("s_waitcnt lgkmcnt(0)" ::: "memory"); SBAR();
;     o[3] = __builtin_amdgcn_mfma_f32_32x32x16_bf16(pa, PK(l3, h3), o[3], 0, 0, 0);
;     ...
; }
; __device__ __forceinline__ void pv_d0(f32x16* o, int vb, bf16x8 pa0, bf16x8 pa1, bf16x8 pa2, bf16x8 pa3) {
;     __builtin_amdgcn_s_setprio(1);
;     pv_ks<0>(o, vb, pa0); pv_ks<1>(o, vb, pa1); pv_ks<2>(o, vb, pa2); pv_ks<3>(o, vb, pa3);
;     __builtin_amdgcn_s_setprio(0);
; }
; __device__ __forceinline__ void exp_half(f32x16& p) {
; #pragma unroll
;     for (int r = 0; r < 16; ++r) p[r] = __builtin_amdgcn_exp2f(p[r]);
; }
; __device__ __forceinline__ void pack_p(const f32x16& p0, const f32x16& p1, float& l_reg, bf16x8& pa0, bf16x8& pa1, bf16x8& pa2, bf16x8& pa3) {
;     float ps = 0;
; #pragma unroll
;     for (int r = 0; r < 16; ++r) ps += p0[r];
; #pragma unroll
;     for (int r = 0; r < 16; ++r) ps += p1[r];
;     l_reg += ps;
;     ...
;     PK4(p0, 0, pa0); PK4(p0, 8, pa1); PK4(p1, 0, pa2); PK4(p1, 8, pa3);
;     ...
; }
; __device__ __forceinline__ void bias_init(f32x16& p0, f32x16& p1, float base, float nslope2, float nM2, int rel  ) {
;     if (rel <= -63 || rel >= 31) {
;         const float sg = (rel < 0) ? -nslope2 : nslope2, lbv = fmaf(-sg, base, nM2);
; #pragma unroll
;         for (int r = 0; r < 16; ++r) { p0[r] = fmaf((float)((r & 3) + 8 * (r >> 2)), sg, lbv); p1[r] = fmaf((float)((r & 3) + 8 * (r >> 2) + 32), sg, lbv); }
;     } else {
; #pragma unroll
	v_mfma_f32_32x32x16_bf16 v[32:47], v[136:139], v[148:151], v[32:47]
	ds_read_b64_tr_b16 v[148:149], v252 offset:12800
	ds_read_b64_tr_b16 v[150:151], v252 offset:14848
	v_fmamk_f32 v65, v185, 0x42040000, v187
	v_fmamk_f32 v66, v185, 0x42080000, v187
	v_fmamk_f32 v67, v185, 0x420c0000, v187
	v_fmamk_f32 v68, v185, 0x42200000, v187
	v_fmamk_f32 v69, v185, 0x42240000, v187
	v_fmamk_f32 v70, v185, 0x42280000, v187
	s_waitcnt lgkmcnt(6)
	v_mfma_f32_32x32x16_bf16 v[16:31], v[136:139], v[152:155], v[16:31]
	ds_read_b64_tr_b16 v[152:153], v252 offset:13312
	ds_read_b64_tr_b16 v[154:155], v252 offset:15360
	v_fmamk_f32 v71, v185, 0x422c0000, v187
	v_fmamk_f32 v72, v185, 0x42400000, v187
	v_fmamk_f32 v73, v185, 0x42440000, v187
	v_fmamk_f32 v74, v185, 0x42480000, v187
	v_fmamk_f32 v75, v185, 0x424c0000, v187
	v_fmamk_f32 v76, v185, 0x42600000, v187
	s_waitcnt lgkmcnt(6)
	v_mfma_f32_32x32x16_bf16 v[0:15], v[136:139], v[156:159], v[0:15]
	ds_read_b64_tr_b16 v[156:157], v252 offset:13824
	ds_read_b64_tr_b16 v[158:159], v252 offset:15872
	v_fmamk_f32 v77, v185, 0x42640000, v187
	v_fmamk_f32 v78, v185, 0x42680000, v187
	v_fmamk_f32 v79, v185, 0x426c0000, v187
	v_exp_f32_e32 v112, v112
	v_exp_f32_e32 v113, v113
	s_waitcnt lgkmcnt(6)
	v_mfma_f32_32x32x16_bf16 v[48:63], v[140:143], v[144:147], v[48:63]
	ds_read_b64_tr_b16 v[144:145], v252 offset:16384
	ds_read_b64_tr_b16 v[146:147], v252 offset:18432
	v_exp_f32_e32 v114, v114
	v_exp_f32_e32 v115, v115
	v_add_f32_e32 v182, v112, v182
	v_add_f32_e32 v182, v113, v182
	s_waitcnt lgkmcnt(6)
	v_mfma_f32_32x32x16_bf16 v[32:47], v[140:143], v[148:151], v[32:47]
	ds_read_b64_tr_b16 v[148:149], v252 offset:16896
	ds_read_b64_tr_b16 v[150:151], v252 offset:18944
	v_cvt_pk_bf16_f32 v128, v112, v113
	v_exp_f32_e32 v116, v116
	v_exp_f32_e32 v117, v117
	v_add_f32_e32 v182, v114, v182
	s_waitcnt lgkmcnt(6)
	v_mfma_f32_32x32x16_bf16 v[16:31], v[140:143], v[152:155], v[16:31]
	ds_read_b64_tr_b16 v[152:153], v252 offset:17408
	ds_read_b64_tr_b16 v[154:155], v252 offset:19456
	v_add_f32_e32 v182, v115, v182
	v_cvt_pk_bf16_f32 v129, v114, v115
	v_exp_f32_e32 v118, v118
	v_exp_f32_e32 v119, v119
	s_waitcnt lgkmcnt(6)
	v_mfma_f32_32x32x16_bf16 v[0:15], v[140:143], v[156:159], v[0:15]
	ds_read_b64_tr_b16 v[156:157], v252 offset:17920
	ds_read_b64_tr_b16 v[158:159], v252 offset:19968
	v_add_f32_e32 v182, v116, v182
	v_add_f32_e32 v182, v117, v182
	v_cvt_pk_bf16_f32 v130, v116, v117
	v_cvt_pk_bf16_f32 v131, v118, v119
	v_add_f32_e32 v182, v118, v182
	v_add_f32_e32 v182, v119, v182
	s_add_i32 s100, s55, 62
	s_cmp_lt_u32 s100, 93
	s_cbranch_scc0 .Lsym_nodiag_s0
	v_add_f32_e32 v190, 0x00000000, v183
	v_add_f32_e32 v191, 0xc2000000, v183
	v_fma_f32 v80, |v190|, v186, s16
	v_fma_f32 v64, |v191|, v186, s16
	v_add_f32_e32 v190, 0xbf800000, v183
	v_add_f32_e32 v191, 0xc2040000, v183
	v_fma_f32 v81, |v190|, v186, s16
	v_fma_f32 v65, |v191|, v186, s16
	v_add_f32_e32 v190, 0xc0000000, v183
	v_add_f32_e32 v191, 0xc2080000, v183
	v_fma_f32 v82, |v190|, v186, s16
	v_fma_f32 v66, |v191|, v186, s16
	v_add_f32_e32 v190, 0xc0400000, v183
	v_add_f32_e32 v191, 0xc20c0000, v183
	v_fma_f32 v83, |v190|, v186, s16
	v_fma_f32 v67, |v191|, v186, s16
	v_add_f32_e32 v190, 0xc1000000, v183
	v_add_f32_e32 v191, 0xc2200000, v183
	v_fma_f32 v84, |v190|, v186, s16
	v_fma_f32 v68, |v191|, v186, s16
	v_add_f32_e32 v190, 0xc1100000, v183
	v_add_f32_e32 v191, 0xc2240000, v183
	v_fma_f32 v85, |v190|, v186, s16
	v_fma_f32 v69, |v191|, v186, s16
	v_add_f32_e32 v190, 0xc1200000, v183
	v_add_f32_e32 v191, 0xc2280000, v183
	v_fma_f32 v86, |v190|, v186, s16
	v_fma_f32 v70, |v191|, v186, s16
	v_add_f32_e32 v190, 0xc1300000, v183
	v_add_f32_e32 v191, 0xc22c0000, v183
	v_fma_f32 v87, |v190|, v186, s16
	v_fma_f32 v71, |v191|, v186, s16
	v_add_f32_e32 v190, 0xc1800000, v183
	v_add_f32_e32 v191, 0xc2400000, v183
	v_fma_f32 v88, |v190|, v186, s16
	v_fma_f32 v72, |v191|, v186, s16
	v_add_f32_e32 v190, 0xc1880000, v183
	v_add_f32_e32 v191, 0xc2440000, v183
	v_fma_f32 v89, |v190|, v186, s16
	v_fma_f32 v73, |v191|, v186, s16
	v_add_f32_e32 v190, 0xc1900000, v183
	v_add_f32_e32 v191, 0xc2480000, v183
	v_fma_f32 v90, |v190|, v186, s16
	v_fma_f32 v74, |v191|, v186, s16
	v_add_f32_e32 v190, 0xc1980000, v183
	v_add_f32_e32 v191, 0xc24c0000, v183
	v_fma_f32 v91, |v190|, v186, s16
	v_fma_f32 v75, |v191|, v186, s16
	v_add_f32_e32 v190, 0xc1c00000, v183
	v_add_f32_e32 v191, 0xc2600000, v183
	v_fma_f32 v92, |v190|, v186, s16
	v_fma_f32 v76, |v191|, v186, s16
	v_add_f32_e32 v190, 0xc1c80000, v183
	v_add_f32_e32 v191, 0xc2640000, v183
	v_fma_f32 v93, |v190|, v186, s16
	v_fma_f32 v77, |v191|, v186, s16
	v_add_f32_e32 v190, 0xc1d00000, v183
	v_add_f32_e32 v191, 0xc2680000, v183
	v_fma_f32 v94, |v190|, v186, s16
	v_fma_f32 v78, |v191|, v186, s16
	v_add_f32_e32 v190, 0xc1d80000, v183
	v_add_f32_e32 v191, 0xc26c0000, v183
	v_fma_f32 v95, |v190|, v186, s16
	v_fma_f32 v79, |v191|, v186, s16

; #define SBAR() __builtin_amdgcn_sched_barrier(0)
; #define PK4(P, BASE, OUT) do { u32x4 w = {cvtpk(P[BASE + 0], P[BASE + 1]), cvtpk(P[BASE + 2], P[BASE + 3]), cvtpk(P[BASE + 4], P[BASE + 5]), cvtpk(P[BASE + 6], P[BASE + 7])}; \
;     OUT = *reinterpret_cast<bf16x8*>(&w); } while (0)
; template <int KS> __device__ __forceinline__ void pv_ks(f32x16* o, int vb, bf16x8 pa) {
;     const s16x4 l0 = tr_read<v_rd_off(0, KS, 0)>(vb), h0 = tr_read<v_rd_off(0, KS, 1)>(vb), l1 = tr_read<v_rd_off(1, KS, 0)>(vb), h1 = tr_read<v_rd_off(1, KS, 1)>(vb);
;     const s16x4 l2 = tr_read<v_rd_off(2, KS, 0)>(vb), h2 = tr_read<v_rd_off(2, KS, 1)>(vb), l3 = tr_read<v_rd_off(3, KS, 0)>(vb), h3 = tr_read<v_rd_off(3, KS, 1)>(vb);
;     ...
;     asm volatile("s_waitcnt lgkmcnt(6)" ::: "memory"); SBAR();
;     o[0] = __builtin_amdgcn_mfma_f32_32x32x16_bf16(pa, PK(l0, h0), o[0], 0, 0, 0);
;     asm volatile("s_waitcnt lgkmcnt(4)" ::: "memory"); SBAR();
;     o[1] = __builtin_amdgcn_mfma_f32_32x32x16_bf16(pa, PK(l1, h1), o[1], 0, 0, 0);
;     asm volatile("s_waitcnt lgkmcnt(2)" ::: "memory"); SBAR();
;     o[2] = __builtin_amdgcn_mfma_f32_32x32x16_bf16(pa, PK(l2, h2), o[2], 0, 0, 0);
;     asm volatile("s_waitcnt lgkmcnt(0)" ::: "memory"); SBAR();
;     o[3] = __builtin_amdgcn_mfma_f32_32x32x16_bf16(pa, PK(l3, h3), o[3], 0, 0, 0);
;     ...
; }
; __device__ __forceinline__ void pv_d0(f32x16* o, int vb, bf16x8 pa0, bf16x8 pa1, bf16x8 pa2, bf16x8 pa3) {
;     __builtin_amdgcn_s_setprio(1);
;     pv_ks<0>(o, vb, pa0); pv_ks<1>(o, vb, pa1); pv_ks<2>(o, vb, pa2); pv_ks<3>(o, vb, pa3);
;     __builtin_amdgcn_s_setprio(0);
; }
; __device__ __forceinline__ void exp_half(f32x16& p) {
; #pragma unroll
;     for (int r = 0; r < 16; ++r) p[r] = __builtin_amdgcn_exp2f(p[r]);
; }
; __device__ __forceinline__ void pack_p(const f32x16& p0, const f32x16& p1, float& l_reg, bf16x8& pa0, bf16x8& pa1, bf16x8& pa2, bf16x8& pa3) {
;     float ps = 0;
; #pragma unroll
;     for (int r = 0; r < 16; ++r) ps += p0[r];
; #pragma unroll
;     for (int r = 0; r < 16; ++r) ps += p1[r];
;     l_reg += ps;
;     ...
;     PK4(p0, 0, pa0); PK4(p0, 8, pa1); PK4(p1, 0, pa2); PK4(p1, 8, pa3);
;     ...
; }
.Lsym_nostage_s1:
	s_waitcnt lgkmcnt(14)
	v_mfma_f32_32x32x16_bf16 v[48:63], v[128:131], v[144:147], v[48:63]
	ds_read_b64_tr_b16 v[144:145], v252 offset:20480
	ds_read_b64_tr_b16 v[146:147], v252 offset:22528
	v_exp_f32_e32 v120, v120
	v_exp_f32_e32 v121, v121
	v_exp_f32_e32 v122, v122
	s_waitcnt lgkmcnt(9)
	v_mfma_f32_32x32x16_bf16 v[80:95], v[192:195], v[172:175], v[80:95]
	v_exp_f32_e32 v123, v123
	v_add_f32_e32 v182, v120, v182
	v_add_f32_e32 v182, v121, v182
	v_cvt_pk_bf16_f32 v132, v120, v121
	v_exp_f32_e32 v124, v124
	v_mfma_f32_32x32x16_bf16 v[32:47], v[128:131], v[148:151], v[32:47]
	ds_read_b64_tr_b16 v[148:149], v252 offset:20992
	ds_read_b64_tr_b16 v[150:151], v252 offset:23040
	v_exp_f32_e32 v125, v125
	v_add_f32_e32 v182, v122, v182
	v_add_f32_e32 v182, v123, v182
	v_cvt_pk_bf16_f32 v133, v122, v123
	s_waitcnt lgkmcnt(10)
	v_mfma_f32_32x32x16_bf16 v[64:79], v[196:199], v[172:175], v[64:79]
	v_exp_f32_e32 v126, v126
	v_exp_f32_e32 v127, v127
	v_add_f32_e32 v182, v124, v182
	v_add_f32_e32 v182, v125, v182
	v_mfma_f32_32x32x16_bf16 v[16:31], v[128:131], v[152:155], v[16:31]
	ds_read_b64_tr_b16 v[152:153], v252 offset:21504
	ds_read_b64_tr_b16 v[154:155], v252 offset:23552
	v_cvt_pk_bf16_f32 v134, v124, v125
	v_cvt_pk_bf16_f32 v135, v126, v127
	v_add_f32_e32 v182, v126, v182
	v_add_f32_e32 v182, v127, v182
	v_exp_f32_e32 v96, v96
	s_waitcnt lgkmcnt(11)
	v_mfma_f32_32x32x16_bf16 v[80:95], v[200:203], v[168:171], v[80:95]
	v_exp_f32_e32 v97, v97
	v_exp_f32_e32 v98, v98
	v_exp_f32_e32 v99, v99
	v_add_f32_e32 v182, v96, v182
	v_mfma_f32_32x32x16_bf16 v[0:15], v[128:131], v[156:159], v[0:15]
	ds_read_b64_tr_b16 v[156:157], v252 offset:22016
	ds_read_b64_tr_b16 v[158:159], v252 offset:24064
	v_add_f32_e32 v182, v97, v182
	v_cvt_pk_bf16_f32 v136, v96, v97
	v_exp_f32_e32 v100, v100
	v_exp_f32_e32 v101, v101
	s_waitcnt lgkmcnt(12)
	v_mfma_f32_32x32x16_bf16 v[64:79], v[204:207], v[168:171], v[64:79]
	v_add_f32_e32 v182, v98, v182
	v_add_f32_e32 v182, v99, v182
	v_cvt_pk_bf16_f32 v137, v98, v99
	v_exp_f32_e32 v102, v102
	s_waitcnt lgkmcnt(6)
	v_mfma_f32_32x32x16_bf16 v[48:63], v[132:135], v[144:147], v[48:63]
	ds_read_b64_tr_b16 v[144:145], v252 offset:24576
	ds_read_b64_tr_b16 v[146:147], v252 offset:26624
	v_exp_f32_e32 v103, v103
	v_add_f32_e32 v182, v100, v182
	v_add_f32_e32 v182, v101, v182
	v_cvt_pk_bf16_f32 v138, v100, v101
	v_cvt_pk_bf16_f32 v139, v102, v103
	v_add_f32_e32 v182, v102, v182
	v_mfma_f32_32x32x16_bf16 v[80:95], v[208:211], v[164:167], v[80:95]
	v_add_f32_e32 v182, v103, v182
	v_exp_f32_e32 v104, v104
	v_exp_f32_e32 v105, v105
	v_exp_f32_e32 v106, v106
	s_waitcnt lgkmcnt(6)
	v_mfma_f32_32x32x16_bf16 v[32:47], v[132:135], v[148:151], v[32:47]
	ds_read_b64_tr_b16 v[148:149], v252 offset:25088
	ds_read_b64_tr_b16 v[150:151], v252 offset:27136
	v_exp_f32_e32 v107, v107
	v_add_f32_e32 v182, v104, v182
	v_add_f32_e32 v182, v105, v182
	v_cvt_pk_bf16_f32 v140, v104, v105
	v_mfma_f32_32x32x16_bf16 v[64:79], v[212:215], v[164:167], v[64:79]
	v_exp_f32_e32 v108, v108
	v_exp_f32_e32 v109, v109
	v_add_f32_e32 v182, v106, v182
	v_add_f32_e32 v182, v107, v182
	s_waitcnt lgkmcnt(6)
	v_mfma_f32_32x32x16_bf16 v[16:31], v[132:135], v[152:155], v[16:31]
	ds_read_b64_tr_b16 v[152:153], v252 offset:25600
	ds_read_b64_tr_b16 v[154:155], v252 offset:27648
	v_cvt_pk_bf16_f32 v141, v106, v107
	v_exp_f32_e32 v110, v110
	v_exp_f32_e32 v111, v111
	v_add_f32_e32 v182, v108, v182
	v_mfma_f32_32x32x16_bf16 v[80:95], v[216:219], v[160:163], v[80:95]
	v_add_f32_e32 v182, v109, v182
	v_cvt_pk_bf16_f32 v142, v108, v109
	v_cvt_pk_bf16_f32 v143, v110, v111
	v_add_f32_e32 v182, v110, v182
	v_add_f32_e32 v182, v111, v182
	s_cmp_lt_i32 s55, 0
	s_cselect_b32 s100, -1.0, 1.0
	v_mul_f32_e32 v185, s100, v186
	s_waitcnt lgkmcnt(6)
	v_mfma_f32_32x32x16_bf16 v[0:15], v[132:135], v[156:159], v[0:15]
	ds_read_b64_tr_b16 v[156:157], v252 offset:26112
	ds_read_b64_tr_b16 v[158:159], v252 offset:28160
	v_fma_f32 v187, -v185, v183, s16
	v_fmamk_f32 v112, v185, 0x00000000, v187
	v_fmamk_f32 v113, v185, 0x3f800000, v187
	v_fmamk_f32 v114, v185, 0x40000000, v187
	v_fmamk_f32 v115, v185, 0x40400000, v187
	v_fmamk_f32 v116, v185, 0x41000000, v187
	v_mfma_f32_32x32x16_bf16 v[64:79], v[220:223], v[160:163], v[64:79]
	v_fmamk_f32 v117, v185, 0x41100000, v187
	v_fmamk_f32 v118, v185, 0x41200000, v187
	v_fmamk_f32 v119, v185, 0x41300000, v187
	v_fmamk_f32 v120, v185, 0x41800000, v187
	v_fmamk_f32 v121, v185, 0x41880000, v187
	v_fmamk_f32 v122, v185, 0x41900000, v187
	s_waitcnt lgkmcnt(6)
	v_mfma_f32_32x32x16_bf16 v[48:63], v[136:139], v[144:147], v[48:63]
	ds_read_b64_tr_b16 v[144:145], v252 offset:28672
	ds_read_b64_tr_b16 v[146:147], v252 offset:30720
	v_fmamk_f32 v123, v185, 0x41980000, v187
	v_fmamk_f32 v124, v185, 0x41c00000, v187
	v_fmamk_f32 v125, v185, 0x41c80000, v187
	v_fmamk_f32 v126, v185, 0x41d00000, v187
	v_fmamk_f32 v127, v185, 0x41d80000, v187
	v_fmamk_f32 v96, v185, 0x42000000, v187
	s_waitcnt lgkmcnt(6)
; #define SBAR() __builtin_amdgcn_sched_barrier(0)
; template <int KS> __device__ __forceinline__ void pv_ks(f32x16* o, int vb, bf16x8 pa) {
;     const s16x4 l0 = tr_read<v_rd_off(0, KS, 0)>(vb), h0 = tr_read<v_rd_off(0, KS, 1)>(vb), l1 = tr_read<v_rd_off(1, KS, 0)>(vb), h1 = tr_read<v_rd_off(1, KS, 1)>(vb);
;     const s16x4 l2 = tr_read<v_rd_off(2, KS, 0)>(vb), h2 = tr_read<v_rd_off(2, KS, 1)>(vb), l3 = tr_read<v_rd_off(3, KS, 0)>(vb), h3 = tr_read<v_rd_off(3, KS, 1)>(vb);
;     ...
;     asm volatile("s_waitcnt lgkmcnt(6)" ::: "memory"); SBAR();
;     o[0] = __builtin_amdgcn_mfma_f32_32x32x16_bf16(pa, PK(l0, h0), o[0], 0, 0, 0);
;     asm volatile("s_waitcnt lgkmcnt(4)" ::: "memory"); SBAR();
;     o[1] = __builtin_amdgcn_mfma_f32_32x32x16_bf16(pa, PK(l1, h1), o[1], 0, 0, 0);
;     asm volatile("s_waitcnt lgkmcnt(2)" ::: "memory"); SBAR();
;     o[2] = __builtin_amdgcn_mfma_f32_32x32x16_bf16(pa, PK(l2, h2), o[2], 0, 0, 0);
;     asm volatile("s_waitcnt lgkmcnt(0)" ::: "memory"); SBAR();
;     o[3] = __builtin_amdgcn_mfma_f32_32x32x16_bf16(pa, PK(l3, h3), o[3], 0, 0, 0);
;     ...
; }
; __device__ __forceinline__ void pv_d0(f32x16* o, int vb, bf16x8 pa0, bf16x8 pa1, bf16x8 pa2, bf16x8 pa3) {
;     __builtin_amdgcn_s_setprio(1);
;     pv_ks<0>(o, vb, pa0); pv_ks<1>(o, vb, pa1); pv_ks<2>(o, vb, pa2); pv_ks<3>(o, vb, pa3);
;     __builtin_amdgcn_s_setprio(0);
; }
; __device__ __forceinline__ void exp_half(f32x16& p) {
; #pragma unroll
;     for (int r = 0; r < 16; ++r) p[r] = __builtin_amdgcn_exp2f(p[r]);
; }
; __device__ __forceinline__ void pack_p(const f32x16& p0, const f32x16& p1, float& l_reg, bf16x8& pa0, bf16x8& pa1, bf16x8& pa2, bf16x8& pa3) {
;     float ps = 0;
; #pragma unroll
;     for (int r = 0; r < 16; ++r) ps += p0[r];
; #pragma unroll
;     for (int r = 0; r < 16; ++r) ps += p1[r];
;     l_reg += ps;
;     ...
;     PK4(p0, 0, pa0); PK4(p0, 8, pa1); PK4(p1, 0, pa2); PK4(p1, 8, pa3);
;     ...
; }
; __device__ __forceinline__ void bias_init(f32x16& p0, f32x16& p1, float base, float nslope2, float nM2, int rel  ) {
;     if (rel <= -63 || rel >= 31) {
;         const float sg = (rel < 0) ? -nslope2 : nslope2, lbv = fmaf(-sg, base, nM2);
; #pragma unroll
;         for (int r = 0; r < 16; ++r) { p0[r] = fmaf((float)((r & 3) + 8 * (r >> 2)), sg, lbv); p1[r] = fmaf((float)((r & 3) + 8 * (r >> 2) + 32), sg, lbv); }
;     } else {
; #pragma unroll
	v_mfma_f32_32x32x16_bf16 v[32:47], v[136:139], v[148:151], v[32:47]
	ds_read_b64_tr_b16 v[148:149], v252 offset:29184
	ds_read_b64_tr_b16 v[150:151], v252 offset:31232
	v_fmamk_f32 v97, v185, 0x42040000, v187
	v_fmamk_f32 v98, v185, 0x42080000, v187
	v_fmamk_f32 v99, v185, 0x420c0000, v187
	v_fmamk_f32 v100, v185, 0x42200000, v187
	v_fmamk_f32 v101, v185, 0x42240000, v187
	v_fmamk_f32 v102, v185, 0x42280000, v187
	s_waitcnt lgkmcnt(6)
	v_mfma_f32_32x32x16_bf16 v[16:31], v[136:139], v[152:155], v[16:31]
	ds_read_b64_tr_b16 v[152:153], v252 offset:29696
	ds_read_b64_tr_b16 v[154:155], v252 offset:31744
	v_fmamk_f32 v103, v185, 0x422c0000, v187
	v_fmamk_f32 v104, v185, 0x42400000, v187
	v_fmamk_f32 v105, v185, 0x42440000, v187
	v_fmamk_f32 v106, v185, 0x42480000, v187
	v_fmamk_f32 v107, v185, 0x424c0000, v187
	v_fmamk_f32 v108, v185, 0x42600000, v187
	s_waitcnt lgkmcnt(6)
	v_mfma_f32_32x32x16_bf16 v[0:15], v[136:139], v[156:159], v[0:15]
	ds_read_b64_tr_b16 v[156:157], v252 offset:30208
	ds_read_b64_tr_b16 v[158:159], v252 offset:32256
	v_fmamk_f32 v109, v185, 0x42640000, v187
	v_fmamk_f32 v110, v185, 0x42680000, v187
	v_fmamk_f32 v111, v185, 0x426c0000, v187
	v_exp_f32_e32 v80, v80
	v_exp_f32_e32 v81, v81
	s_waitcnt lgkmcnt(6)
	v_mfma_f32_32x32x16_bf16 v[48:63], v[140:143], v[144:147], v[48:63]
	ds_read_b64_tr_b16 v[144:145], v252 offset:32768
	ds_read_b64_tr_b16 v[146:147], v252 offset:34816
	v_exp_f32_e32 v82, v82
	v_exp_f32_e32 v83, v83
	v_add_f32_e32 v182, v80, v182
	v_add_f32_e32 v182, v81, v182
	s_waitcnt lgkmcnt(6)
	v_mfma_f32_32x32x16_bf16 v[32:47], v[140:143], v[148:151], v[32:47]
	ds_read_b64_tr_b16 v[148:149], v252 offset:33280
	ds_read_b64_tr_b16 v[150:151], v252 offset:35328
	v_cvt_pk_bf16_f32 v128, v80, v81
	v_exp_f32_e32 v84, v84
	v_exp_f32_e32 v85, v85
	v_add_f32_e32 v182, v82, v182
	s_waitcnt lgkmcnt(6)
	v_mfma_f32_32x32x16_bf16 v[16:31], v[140:143], v[152:155], v[16:31]
	ds_read_b64_tr_b16 v[152:153], v252 offset:33792
	ds_read_b64_tr_b16 v[154:155], v252 offset:35840
	v_add_f32_e32 v182, v83, v182
	v_cvt_pk_bf16_f32 v129, v82, v83
	v_exp_f32_e32 v86, v86
	v_exp_f32_e32 v87, v87
	s_waitcnt lgkmcnt(6)
	v_mfma_f32_32x32x16_bf16 v[0:15], v[140:143], v[156:159], v[0:15]
	ds_read_b64_tr_b16 v[156:157], v252 offset:34304
	ds_read_b64_tr_b16 v[158:159], v252 offset:36352
	v_add_f32_e32 v182, v84, v182
	v_add_f32_e32 v182, v85, v182
	v_cvt_pk_bf16_f32 v130, v84, v85
	v_cvt_pk_bf16_f32 v131, v86, v87
	v_add_f32_e32 v182, v86, v182
	v_add_f32_e32 v182, v87, v182
	s_add_i32 s100, s55, 62
	s_cmp_lt_u32 s100, 93
	s_cbranch_scc0 .Lsym_nodiag_s1
	v_add_f32_e32 v190, 0x00000000, v183
	v_add_f32_e32 v191, 0xc2000000, v183
	v_fma_f32 v112, |v190|, v186, s16
	v_fma_f32 v96, |v191|, v186, s16
	v_add_f32_e32 v190, 0xbf800000, v183
	v_add_f32_e32 v191, 0xc2040000, v183
	v_fma_f32 v113, |v190|, v186, s16
	v_fma_f32 v97, |v191|, v186, s16
	v_add_f32_e32 v190, 0xc0000000, v183
	v_add_f32_e32 v191, 0xc2080000, v183
	v_fma_f32 v114, |v190|, v186, s16
	v_fma_f32 v98, |v191|, v186, s16
	v_add_f32_e32 v190, 0xc0400000, v183
	v_add_f32_e32 v191, 0xc20c0000, v183
	v_fma_f32 v115, |v190|, v186, s16
	v_fma_f32 v99, |v191|, v186, s16
	v_add_f32_e32 v190, 0xc1000000, v183
	v_add_f32_e32 v191, 0xc2200000, v183
	v_fma_f32 v116, |v190|, v186, s16
	v_fma_f32 v100, |v191|, v186, s16
	v_add_f32_e32 v190, 0xc1100000, v183
	v_add_f32_e32 v191, 0xc2240000, v183
	v_fma_f32 v117, |v190|, v186, s16
	v_fma_f32 v101, |v191|, v186, s16
	v_add_f32_e32 v190, 0xc1200000, v183
	v_add_f32_e32 v191, 0xc2280000, v183
	v_fma_f32 v118, |v190|, v186, s16
	v_fma_f32 v102, |v191|, v186, s16
	v_add_f32_e32 v190, 0xc1300000, v183
	v_add_f32_e32 v191, 0xc22c0000, v183
	v_fma_f32 v119, |v190|, v186, s16
	v_fma_f32 v103, |v191|, v186, s16
	v_add_f32_e32 v190, 0xc1800000, v183
	v_add_f32_e32 v191, 0xc2400000, v183
	v_fma_f32 v120, |v190|, v186, s16
	v_fma_f32 v104, |v191|, v186, s16
	v_add_f32_e32 v190, 0xc1880000, v183
	v_add_f32_e32 v191, 0xc2440000, v183
	v_fma_f32 v121, |v190|, v186, s16
	v_fma_f32 v105, |v191|, v186, s16
	v_add_f32_e32 v190, 0xc1900000, v183
	v_add_f32_e32 v191, 0xc2480000, v183
	v_fma_f32 v122, |v190|, v186, s16
	v_fma_f32 v106, |v191|, v186, s16
	v_add_f32_e32 v190, 0xc1980000, v183
	v_add_f32_e32 v191, 0xc24c0000, v183
	v_fma_f32 v123, |v190|, v186, s16
	v_fma_f32 v107, |v191|, v186, s16
	v_add_f32_e32 v190, 0xc1c00000, v183
	v_add_f32_e32 v191, 0xc2600000, v183
	v_fma_f32 v124, |v190|, v186, s16
	v_fma_f32 v108, |v191|, v186, s16
	v_add_f32_e32 v190, 0xc1c80000, v183
	v_add_f32_e32 v191, 0xc2640000, v183
	v_fma_f32 v125, |v190|, v186, s16
	v_fma_f32 v109, |v191|, v186, s16
	v_add_f32_e32 v190, 0xc1d00000, v183
	v_add_f32_e32 v191, 0xc2680000, v183
	v_fma_f32 v126, |v190|, v186, s16
	v_fma_f32 v110, |v191|, v186, s16
	v_add_f32_e32 v190, 0xc1d80000, v183
	v_add_f32_e32 v191, 0xc26c0000, v183
	v_fma_f32 v127, |v190|, v186, s16
	v_fma_f32 v111, |v191|, v186, s16

; #define SBAR() __builtin_amdgcn_sched_barrier(0)
; #define PK4(P, BASE, OUT) do { u32x4 w = {cvtpk(P[BASE + 0], P[BASE + 1]), cvtpk(P[BASE + 2], P[BASE + 3]), cvtpk(P[BASE + 4], P[BASE + 5]), cvtpk(P[BASE + 6], P[BASE + 7])}; \
;     OUT = *reinterpret_cast<bf16x8*>(&w); } while (0)
; template <int KS> __device__ __forceinline__ void pv_ks(f32x16* o, int vb, bf16x8 pa) {
;     const s16x4 l0 = tr_read<v_rd_off(0, KS, 0)>(vb), h0 = tr_read<v_rd_off(0, KS, 1)>(vb), l1 = tr_read<v_rd_off(1, KS, 0)>(vb), h1 = tr_read<v_rd_off(1, KS, 1)>(vb);
;     const s16x4 l2 = tr_read<v_rd_off(2, KS, 0)>(vb), h2 = tr_read<v_rd_off(2, KS, 1)>(vb), l3 = tr_read<v_rd_off(3, KS, 0)>(vb), h3 = tr_read<v_rd_off(3, KS, 1)>(vb);
;     ...
;     asm volatile("s_waitcnt lgkmcnt(6)" ::: "memory"); SBAR();
;     o[0] = __builtin_amdgcn_mfma_f32_32x32x16_bf16(pa, PK(l0, h0), o[0], 0, 0, 0);
;     asm volatile("s_waitcnt lgkmcnt(4)" ::: "memory"); SBAR();
;     o[1] = __builtin_amdgcn_mfma_f32_32x32x16_bf16(pa, PK(l1, h1), o[1], 0, 0, 0);
;     asm volatile("s_waitcnt lgkmcnt(2)" ::: "memory"); SBAR();
;     o[2] = __builtin_amdgcn_mfma_f32_32x32x16_bf16(pa, PK(l2, h2), o[2], 0, 0, 0);
;     asm volatile("s_waitcnt lgkmcnt(0)" ::: "memory"); SBAR();
;     o[3] = __builtin_amdgcn_mfma_f32_32x32x16_bf16(pa, PK(l3, h3), o[3], 0, 0, 0);
;     ...
; }
; __device__ __forceinline__ void pv_d0(f32x16* o, int vb, bf16x8 pa0, bf16x8 pa1, bf16x8 pa2, bf16x8 pa3) {
;     __builtin_amdgcn_s_setprio(1);
;     pv_ks<0>(o, vb, pa0); pv_ks<1>(o, vb, pa1); pv_ks<2>(o, vb, pa2); pv_ks<3>(o, vb, pa3);
;     __builtin_amdgcn_s_setprio(0);
; }
; __device__ __forceinline__ void exp_half(f32x16& p) {
; #pragma unroll
;     for (int r = 0; r < 16; ++r) p[r] = __builtin_amdgcn_exp2f(p[r]);
; }
; __device__ __forceinline__ void pack_p(const f32x16& p0, const f32x16& p1, float& l_reg, bf16x8& pa0, bf16x8& pa1, bf16x8& pa2, bf16x8& pa3) {
;     float ps = 0;
; #pragma unroll
;     for (int r = 0; r < 16; ++r) ps += p0[r];
; #pragma unroll
;     for (int r = 0; r < 16; ++r) ps += p1[r];
;     l_reg += ps;
;     ...
;     PK4(p0, 0, pa0); PK4(p0, 8, pa1); PK4(p1, 0, pa2); PK4(p1, 8, pa3);
;     ...
; }
.Lsym_nostage_s2:
	s_waitcnt lgkmcnt(14)
	v_mfma_f32_32x32x16_bf16 v[48:63], v[128:131], v[144:147], v[48:63]
	ds_read_b64_tr_b16 v[144:145], v252 offset:36864
	ds_read_b64_tr_b16 v[146:147], v252 offset:38912
	v_exp_f32_e32 v88, v88
	v_exp_f32_e32 v89, v89
	v_exp_f32_e32 v90, v90
	s_waitcnt lgkmcnt(9)
	v_mfma_f32_32x32x16_bf16 v[112:127], v[192:195], v[172:175], v[112:127]
	v_exp_f32_e32 v91, v91
	v_add_f32_e32 v182, v88, v182
	v_add_f32_e32 v182, v89, v182
	v_cvt_pk_bf16_f32 v132, v88, v89
	v_exp_f32_e32 v92, v92
	v_mfma_f32_32x32x16_bf16 v[32:47], v[128:131], v[148:151], v[32:47]
	ds_read_b64_tr_b16 v[148:149], v252 offset:37376
	ds_read_b64_tr_b16 v[150:151], v252 offset:39424
	v_exp_f32_e32 v93, v93
	v_add_f32_e32 v182, v90, v182
	v_add_f32_e32 v182, v91, v182
	v_cvt_pk_bf16_f32 v133, v90, v91
	s_waitcnt lgkmcnt(10)
	v_mfma_f32_32x32x16_bf16 v[96:111], v[196:199], v[172:175], v[96:111]
	v_exp_f32_e32 v94, v94
	v_exp_f32_e32 v95, v95
	v_add_f32_e32 v182, v92, v182
	v_add_f32_e32 v182, v93, v182
	v_mfma_f32_32x32x16_bf16 v[16:31], v[128:131], v[152:155], v[16:31]
	ds_read_b64_tr_b16 v[152:153], v252 offset:37888
	ds_read_b64_tr_b16 v[154:155], v252 offset:39936
	v_cvt_pk_bf16_f32 v134, v92, v93
	v_cvt_pk_bf16_f32 v135, v94, v95
	v_add_f32_e32 v182, v94, v182
	v_add_f32_e32 v182, v95, v182
	v_exp_f32_e32 v64, v64
	s_waitcnt lgkmcnt(11)
	v_mfma_f32_32x32x16_bf16 v[112:127], v[200:203], v[168:171], v[112:127]
	v_exp_f32_e32 v65, v65
	v_exp_f32_e32 v66, v66
	v_exp_f32_e32 v67, v67
	v_add_f32_e32 v182, v64, v182
	v_mfma_f32_32x32x16_bf16 v[0:15], v[128:131], v[156:159], v[0:15]
	ds_read_b64_tr_b16 v[156:157], v252 offset:38400
	ds_read_b64_tr_b16 v[158:159], v252 offset:40448
	v_add_f32_e32 v182, v65, v182
	v_cvt_pk_bf16_f32 v136, v64, v65
	v_exp_f32_e32 v68, v68
	v_exp_f32_e32 v69, v69
	s_waitcnt lgkmcnt(12)
	v_mfma_f32_32x32x16_bf16 v[96:111], v[204:207], v[168:171], v[96:111]
	v_add_f32_e32 v182, v66, v182
	v_add_f32_e32 v182, v67, v182
	v_cvt_pk_bf16_f32 v137, v66, v67
	v_exp_f32_e32 v70, v70
	s_waitcnt lgkmcnt(6)
	v_mfma_f32_32x32x16_bf16 v[48:63], v[132:135], v[144:147], v[48:63]
	ds_read_b64_tr_b16 v[144:145], v252 offset:40960
	ds_read_b64_tr_b16 v[146:147], v252 offset:43008
	v_exp_f32_e32 v71, v71
	v_add_f32_e32 v182, v68, v182
	v_add_f32_e32 v182, v69, v182
	v_cvt_pk_bf16_f32 v138, v68, v69
	v_cvt_pk_bf16_f32 v139, v70, v71
	v_add_f32_e32 v182, v70, v182
	v_mfma_f32_32x32x16_bf16 v[112:127], v[208:211], v[164:167], v[112:127]
	v_add_f32_e32 v182, v71, v182
	v_exp_f32_e32 v72, v72
	v_exp_f32_e32 v73, v73
	v_exp_f32_e32 v74, v74
	s_waitcnt lgkmcnt(6)
	v_mfma_f32_32x32x16_bf16 v[32:47], v[132:135], v[148:151], v[32:47]
	ds_read_b64_tr_b16 v[148:149], v252 offset:41472
	ds_read_b64_tr_b16 v[150:151], v252 offset:43520
	v_exp_f32_e32 v75, v75
	v_add_f32_e32 v182, v72, v182
	v_add_f32_e32 v182, v73, v182
	v_cvt_pk_bf16_f32 v140, v72, v73
	v_mfma_f32_32x32x16_bf16 v[96:111], v[212:215], v[164:167], v[96:111]
	v_exp_f32_e32 v76, v76
	v_exp_f32_e32 v77, v77
	v_add_f32_e32 v182, v74, v182
	v_add_f32_e32 v182, v75, v182
	s_waitcnt lgkmcnt(6)
	v_mfma_f32_32x32x16_bf16 v[16:31], v[132:135], v[152:155], v[16:31]
	ds_read_b64_tr_b16 v[152:153], v252 offset:41984
	ds_read_b64_tr_b16 v[154:155], v252 offset:44032
	v_cvt_pk_bf16_f32 v141, v74, v75
	v_exp_f32_e32 v78, v78
	v_exp_f32_e32 v79, v79
	v_add_f32_e32 v182, v76, v182
	v_mfma_f32_32x32x16_bf16 v[112:127], v[216:219], v[160:163], v[112:127]
	v_add_f32_e32 v182, v77, v182
	v_cvt_pk_bf16_f32 v142, v76, v77
	v_cvt_pk_bf16_f32 v143, v78, v79
	v_add_f32_e32 v182, v78, v182
	v_add_f32_e32 v182, v79, v182
	s_cmp_lt_i32 s55, 0
	s_cselect_b32 s100, -1.0, 1.0
	v_mul_f32_e32 v185, s100, v186
	s_waitcnt lgkmcnt(6)
	v_mfma_f32_32x32x16_bf16 v[0:15], v[132:135], v[156:159], v[0:15]
	ds_read_b64_tr_b16 v[156:157], v252 offset:42496
	ds_read_b64_tr_b16 v[158:159], v252 offset:44544
	v_fma_f32 v187, -v185, v183, s16
	v_fmamk_f32 v80, v185, 0x00000000, v187
	v_fmamk_f32 v81, v185, 0x3f800000, v187
	v_fmamk_f32 v82, v185, 0x40000000, v187
	v_fmamk_f32 v83, v185, 0x40400000, v187
	v_fmamk_f32 v84, v185, 0x41000000, v187
	v_mfma_f32_32x32x16_bf16 v[96:111], v[220:223], v[160:163], v[96:111]
	v_fmamk_f32 v85, v185, 0x41100000, v187
	v_fmamk_f32 v86, v185, 0x41200000, v187
	v_fmamk_f32 v87, v185, 0x41300000, v187
	v_fmamk_f32 v88, v185, 0x41800000, v187
	v_fmamk_f32 v89, v185, 0x41880000, v187
	v_fmamk_f32 v90, v185, 0x41900000, v187
	s_waitcnt lgkmcnt(6)
	v_mfma_f32_32x32x16_bf16 v[48:63], v[136:139], v[144:147], v[48:63]
	ds_read_b64_tr_b16 v[144:145], v252 offset:45056
	ds_read_b64_tr_b16 v[146:147], v252 offset:47104
	v_fmamk_f32 v91, v185, 0x41980000, v187
	v_fmamk_f32 v92, v185, 0x41c00000, v187
	v_fmamk_f32 v93, v185, 0x41c80000, v187
	v_fmamk_f32 v94, v185, 0x41d00000, v187
	v_fmamk_f32 v95, v185, 0x41d80000, v187
	v_fmamk_f32 v64, v185, 0x42000000, v187
	s_waitcnt lgkmcnt(6)
; #define SBAR() __builtin_amdgcn_sched_barrier(0)
; template <int KS> __device__ __forceinline__ void pv_ks(f32x16* o, int vb, bf16x8 pa) {
;     const s16x4 l0 = tr_read<v_rd_off(0, KS, 0)>(vb), h0 = tr_read<v_rd_off(0, KS, 1)>(vb), l1 = tr_read<v_rd_off(1, KS, 0)>(vb), h1 = tr_read<v_rd_off(1, KS, 1)>(vb);
;     const s16x4 l2 = tr_read<v_rd_off(2, KS, 0)>(vb), h2 = tr_read<v_rd_off(2, KS, 1)>(vb), l3 = tr_read<v_rd_off(3, KS, 0)>(vb), h3 = tr_read<v_rd_off(3, KS, 1)>(vb);
;     ...
;     asm volatile("s_waitcnt lgkmcnt(6)" ::: "memory"); SBAR();
;     o[0] = __builtin_amdgcn_mfma_f32_32x32x16_bf16(pa, PK(l0, h0), o[0], 0, 0, 0);
;     asm volatile("s_waitcnt lgkmcnt(4)" ::: "memory"); SBAR();
;     o[1] = __builtin_amdgcn_mfma_f32_32x32x16_bf16(pa, PK(l1, h1), o[1], 0, 0, 0);
;     asm volatile("s_waitcnt lgkmcnt(2)" ::: "memory"); SBAR();
;     o[2] = __builtin_amdgcn_mfma_f32_32x32x16_bf16(pa, PK(l2, h2), o[2], 0, 0, 0);
;     asm volatile("s_waitcnt lgkmcnt(0)" ::: "memory"); SBAR();
;     o[3] = __builtin_amdgcn_mfma_f32_32x32x16_bf16(pa, PK(l3, h3), o[3], 0, 0, 0);
;     ...
; }
; __device__ __forceinline__ void pv_d0(f32x16* o, int vb, bf16x8 pa0, bf16x8 pa1, bf16x8 pa2, bf16x8 pa3) {
;     __builtin_amdgcn_s_setprio(1);
;     pv_ks<0>(o, vb, pa0); pv_ks<1>(o, vb, pa1); pv_ks<2>(o, vb, pa2); pv_ks<3>(o, vb, pa3);
;     __builtin_amdgcn_s_setprio(0);
; }
; __device__ __forceinline__ void exp_half(f32x16& p) {
; #pragma unroll
;     for (int r = 0; r < 16; ++r) p[r] = __builtin_amdgcn_exp2f(p[r]);
; }
; __device__ __forceinline__ void pack_p(const f32x16& p0, const f32x16& p1, float& l_reg, bf16x8& pa0, bf16x8& pa1, bf16x8& pa2, bf16x8& pa3) {
;     float ps = 0;
; #pragma unroll
;     for (int r = 0; r < 16; ++r) ps += p0[r];
; #pragma unroll
;     for (int r = 0; r < 16; ++r) ps += p1[r];
;     l_reg += ps;
;     ...
;     PK4(p0, 0, pa0); PK4(p0, 8, pa1); PK4(p1, 0, pa2); PK4(p1, 8, pa3);
;     ...
; }
; __device__ __forceinline__ void bias_init(f32x16& p0, f32x16& p1, float base, float nslope2, float nM2, int rel  ) {
;     if (rel <= -63 || rel >= 31) {
;         const float sg = (rel < 0) ? -nslope2 : nslope2, lbv = fmaf(-sg, base, nM2);
; #pragma unroll
;         for (int r = 0; r < 16; ++r) { p0[r] = fmaf((float)((r & 3) + 8 * (r >> 2)), sg, lbv); p1[r] = fmaf((float)((r & 3) + 8 * (r >> 2) + 32), sg, lbv); }
;     } else {
; #pragma unroll
	v_mfma_f32_32x32x16_bf16 v[32:47], v[136:139], v[148:151], v[32:47]
	ds_read_b64_tr_b16 v[148:149], v252 offset:45568
	ds_read_b64_tr_b16 v[150:151], v252 offset:47616
	v_fmamk_f32 v65, v185, 0x42040000, v187
	v_fmamk_f32 v66, v185, 0x42080000, v187
	v_fmamk_f32 v67, v185, 0x420c0000, v187
	v_fmamk_f32 v68, v185, 0x42200000, v187
	v_fmamk_f32 v69, v185, 0x42240000, v187
	v_fmamk_f32 v70, v185, 0x42280000, v187
	s_waitcnt lgkmcnt(6)
	v_mfma_f32_32x32x16_bf16 v[16:31], v[136:139], v[152:155], v[16:31]
	ds_read_b64_tr_b16 v[152:153], v252 offset:46080
	ds_read_b64_tr_b16 v[154:155], v252 offset:48128
	v_fmamk_f32 v71, v185, 0x422c0000, v187
	v_fmamk_f32 v72, v185, 0x42400000, v187
	v_fmamk_f32 v73, v185, 0x42440000, v187
	v_fmamk_f32 v74, v185, 0x42480000, v187
	v_fmamk_f32 v75, v185, 0x424c0000, v187
	v_fmamk_f32 v76, v185, 0x42600000, v187
	s_waitcnt lgkmcnt(6)
	v_mfma_f32_32x32x16_bf16 v[0:15], v[136:139], v[156:159], v[0:15]
	ds_read_b64_tr_b16 v[156:157], v252 offset:46592
	ds_read_b64_tr_b16 v[158:159], v252 offset:48640
	v_fmamk_f32 v77, v185, 0x42640000, v187
	v_fmamk_f32 v78, v185, 0x42680000, v187
	v_fmamk_f32 v79, v185, 0x426c0000, v187
	v_exp_f32_e32 v112, v112
	v_exp_f32_e32 v113, v113
	s_waitcnt lgkmcnt(6)
	v_mfma_f32_32x32x16_bf16 v[48:63], v[140:143], v[144:147], v[48:63]
	ds_read_b64_tr_b16 v[144:145], v252 offset:49152
	ds_read_b64_tr_b16 v[146:147], v252 offset:51200
	v_exp_f32_e32 v114, v114
	v_exp_f32_e32 v115, v115
	v_add_f32_e32 v182, v112, v182
	v_add_f32_e32 v182, v113, v182
	s_waitcnt lgkmcnt(6)
	v_mfma_f32_32x32x16_bf16 v[32:47], v[140:143], v[148:151], v[32:47]
	ds_read_b64_tr_b16 v[148:149], v252 offset:49664
	ds_read_b64_tr_b16 v[150:151], v252 offset:51712
	v_cvt_pk_bf16_f32 v128, v112, v113
	v_exp_f32_e32 v116, v116
	v_exp_f32_e32 v117, v117
	v_add_f32_e32 v182, v114, v182
	s_waitcnt lgkmcnt(6)
	v_mfma_f32_32x32x16_bf16 v[16:31], v[140:143], v[152:155], v[16:31]
	ds_read_b64_tr_b16 v[152:153], v252 offset:50176
	ds_read_b64_tr_b16 v[154:155], v252 offset:52224
	v_add_f32_e32 v182, v115, v182
	v_cvt_pk_bf16_f32 v129, v114, v115
	v_exp_f32_e32 v118, v118
	v_exp_f32_e32 v119, v119
	s_waitcnt lgkmcnt(6)
	v_mfma_f32_32x32x16_bf16 v[0:15], v[140:143], v[156:159], v[0:15]
	ds_read_b64_tr_b16 v[156:157], v252 offset:50688
	ds_read_b64_tr_b16 v[158:159], v252 offset:52736
	v_add_f32_e32 v182, v116, v182
	v_add_f32_e32 v182, v117, v182
	v_cvt_pk_bf16_f32 v130, v116, v117
	v_cvt_pk_bf16_f32 v131, v118, v119
	v_add_f32_e32 v182, v118, v182
	v_add_f32_e32 v182, v119, v182
	s_add_i32 s100, s55, 62
	s_cmp_lt_u32 s100, 93
	s_cbranch_scc0 .Lsym_nodiag_s2
	v_add_f32_e32 v190, 0x00000000, v183
	v_add_f32_e32 v191, 0xc2000000, v183
	v_fma_f32 v80, |v190|, v186, s16
	v_fma_f32 v64, |v191|, v186, s16
	v_add_f32_e32 v190, 0xbf800000, v183
	v_add_f32_e32 v191, 0xc2040000, v183
	v_fma_f32 v81, |v190|, v186, s16
	v_fma_f32 v65, |v191|, v186, s16
	v_add_f32_e32 v190, 0xc0000000, v183
	v_add_f32_e32 v191, 0xc2080000, v183
	v_fma_f32 v82, |v190|, v186, s16
	v_fma_f32 v66, |v191|, v186, s16
	v_add_f32_e32 v190, 0xc0400000, v183
	v_add_f32_e32 v191, 0xc20c0000, v183
	v_fma_f32 v83, |v190|, v186, s16
	v_fma_f32 v67, |v191|, v186, s16
	v_add_f32_e32 v190, 0xc1000000, v183
	v_add_f32_e32 v191, 0xc2200000, v183
	v_fma_f32 v84, |v190|, v186, s16
	v_fma_f32 v68, |v191|, v186, s16
	v_add_f32_e32 v190, 0xc1100000, v183
	v_add_f32_e32 v191, 0xc2240000, v183
	v_fma_f32 v85, |v190|, v186, s16
	v_fma_f32 v69, |v191|, v186, s16
	v_add_f32_e32 v190, 0xc1200000, v183
	v_add_f32_e32 v191, 0xc2280000, v183
	v_fma_f32 v86, |v190|, v186, s16
	v_fma_f32 v70, |v191|, v186, s16
	v_add_f32_e32 v190, 0xc1300000, v183
	v_add_f32_e32 v191, 0xc22c0000, v183
	v_fma_f32 v87, |v190|, v186, s16
	v_fma_f32 v71, |v191|, v186, s16
	v_add_f32_e32 v190, 0xc1800000, v183
	v_add_f32_e32 v191, 0xc2400000, v183
	v_fma_f32 v88, |v190|, v186, s16
	v_fma_f32 v72, |v191|, v186, s16
	v_add_f32_e32 v190, 0xc1880000, v183
	v_add_f32_e32 v191, 0xc2440000, v183
	v_fma_f32 v89, |v190|, v186, s16
	v_fma_f32 v73, |v191|, v186, s16
	v_add_f32_e32 v190, 0xc1900000, v183
	v_add_f32_e32 v191, 0xc2480000, v183
	v_fma_f32 v90, |v190|, v186, s16
	v_fma_f32 v74, |v191|, v186, s16
	v_add_f32_e32 v190, 0xc1980000, v183
	v_add_f32_e32 v191, 0xc24c0000, v183
	v_fma_f32 v91, |v190|, v186, s16
	v_fma_f32 v75, |v191|, v186, s16
	v_add_f32_e32 v190, 0xc1c00000, v183
	v_add_f32_e32 v191, 0xc2600000, v183
	v_fma_f32 v92, |v190|, v186, s16
	v_fma_f32 v76, |v191|, v186, s16
	v_add_f32_e32 v190, 0xc1c80000, v183
	v_add_f32_e32 v191, 0xc2640000, v183
	v_fma_f32 v93, |v190|, v186, s16
	v_fma_f32 v77, |v191|, v186, s16
	v_add_f32_e32 v190, 0xc1d00000, v183
	v_add_f32_e32 v191, 0xc2680000, v183
	v_fma_f32 v94, |v190|, v186, s16
	v_fma_f32 v78, |v191|, v186, s16
	v_add_f32_e32 v190, 0xc1d80000, v183
	v_add_f32_e32 v191, 0xc26c0000, v183
	v_fma_f32 v95, |v190|, v186, s16
	v_fma_f32 v79, |v191|, v186, s16

; #define SBAR() __builtin_amdgcn_sched_barrier(0)
; #define PK4(P, BASE, OUT) do { u32x4 w = {cvtpk(P[BASE + 0], P[BASE + 1]), cvtpk(P[BASE + 2], P[BASE + 3]), cvtpk(P[BASE + 4], P[BASE + 5]), cvtpk(P[BASE + 6], P[BASE + 7])}; \
;     OUT = *reinterpret_cast<bf16x8*>(&w); } while (0)
; template <int KS> __device__ __forceinline__ void pv_ks(f32x16* o, int vb, bf16x8 pa) {
;     const s16x4 l0 = tr_read<v_rd_off(0, KS, 0)>(vb), h0 = tr_read<v_rd_off(0, KS, 1)>(vb), l1 = tr_read<v_rd_off(1, KS, 0)>(vb), h1 = tr_read<v_rd_off(1, KS, 1)>(vb);
;     const s16x4 l2 = tr_read<v_rd_off(2, KS, 0)>(vb), h2 = tr_read<v_rd_off(2, KS, 1)>(vb), l3 = tr_read<v_rd_off(3, KS, 0)>(vb), h3 = tr_read<v_rd_off(3, KS, 1)>(vb);
;     ...
;     asm volatile("s_waitcnt lgkmcnt(6)" ::: "memory"); SBAR();
;     o[0] = __builtin_amdgcn_mfma_f32_32x32x16_bf16(pa, PK(l0, h0), o[0], 0, 0, 0);
;     asm volatile("s_waitcnt lgkmcnt(4)" ::: "memory"); SBAR();
;     o[1] = __builtin_amdgcn_mfma_f32_32x32x16_bf16(pa, PK(l1, h1), o[1], 0, 0, 0);
;     asm volatile("s_waitcnt lgkmcnt(2)" ::: "memory"); SBAR();
;     o[2] = __builtin_amdgcn_mfma_f32_32x32x16_bf16(pa, PK(l2, h2), o[2], 0, 0, 0);
;     asm volatile("s_waitcnt lgkmcnt(0)" ::: "memory"); SBAR();
;     o[3] = __builtin_amdgcn_mfma_f32_32x32x16_bf16(pa, PK(l3, h3), o[3], 0, 0, 0);
;     ...
; }
; __device__ __forceinline__ void pv_d0(f32x16* o, int vb, bf16x8 pa0, bf16x8 pa1, bf16x8 pa2, bf16x8 pa3) {
;     __builtin_amdgcn_s_setprio(1);
;     pv_ks<0>(o, vb, pa0); pv_ks<1>(o, vb, pa1); pv_ks<2>(o, vb, pa2); pv_ks<3>(o, vb, pa3);
;     __builtin_amdgcn_s_setprio(0);
; }
; __device__ __forceinline__ void exp_half(f32x16& p) {
; #pragma unroll
;     for (int r = 0; r < 16; ++r) p[r] = __builtin_amdgcn_exp2f(p[r]);
; }
; __device__ __forceinline__ void pack_p(const f32x16& p0, const f32x16& p1, float& l_reg, bf16x8& pa0, bf16x8& pa1, bf16x8& pa2, bf16x8& pa3) {
;     float ps = 0;
; #pragma unroll
;     for (int r = 0; r < 16; ++r) ps += p0[r];
; #pragma unroll
;     for (int r = 0; r < 16; ++r) ps += p1[r];
;     l_reg += ps;
;     ...
;     PK4(p0, 0, pa0); PK4(p0, 8, pa1); PK4(p1, 0, pa2); PK4(p1, 8, pa3);
;     ...
; }
.Lsym_nostage_s3:
	s_waitcnt lgkmcnt(14)
	v_mfma_f32_32x32x16_bf16 v[48:63], v[128:131], v[144:147], v[48:63]
	ds_read_b64_tr_b16 v[144:145], v252 offset:53248
	ds_read_b64_tr_b16 v[146:147], v252 offset:55296
	v_exp_f32_e32 v120, v120
	v_exp_f32_e32 v121, v121
	v_exp_f32_e32 v122, v122
	s_waitcnt lgkmcnt(9)
	v_mfma_f32_32x32x16_bf16 v[80:95], v[192:195], v[172:175], v[80:95]
	v_exp_f32_e32 v123, v123
	v_add_f32_e32 v182, v120, v182
	v_add_f32_e32 v182, v121, v182
	v_cvt_pk_bf16_f32 v132, v120, v121
	v_exp_f32_e32 v124, v124
	v_mfma_f32_32x32x16_bf16 v[32:47], v[128:131], v[148:151], v[32:47]
	ds_read_b64_tr_b16 v[148:149], v252 offset:53760
	ds_read_b64_tr_b16 v[150:151], v252 offset:55808
	v_exp_f32_e32 v125, v125
	v_add_f32_e32 v182, v122, v182
	v_add_f32_e32 v182, v123, v182
	v_cvt_pk_bf16_f32 v133, v122, v123
	s_waitcnt lgkmcnt(10)
	v_mfma_f32_32x32x16_bf16 v[64:79], v[196:199], v[172:175], v[64:79]
	v_exp_f32_e32 v126, v126
	v_exp_f32_e32 v127, v127
	v_add_f32_e32 v182, v124, v182
	v_add_f32_e32 v182, v125, v182
	v_mfma_f32_32x32x16_bf16 v[16:31], v[128:131], v[152:155], v[16:31]
	ds_read_b64_tr_b16 v[152:153], v252 offset:54272
	ds_read_b64_tr_b16 v[154:155], v252 offset:56320
	v_cvt_pk_bf16_f32 v134, v124, v125
	v_cvt_pk_bf16_f32 v135, v126, v127
	v_add_f32_e32 v182, v126, v182
	v_add_f32_e32 v182, v127, v182
	v_exp_f32_e32 v96, v96
	s_waitcnt lgkmcnt(11)
	v_mfma_f32_32x32x16_bf16 v[80:95], v[200:203], v[168:171], v[80:95]
	v_exp_f32_e32 v97, v97
	v_exp_f32_e32 v98, v98
	v_exp_f32_e32 v99, v99
	v_add_f32_e32 v182, v96, v182
	v_mfma_f32_32x32x16_bf16 v[0:15], v[128:131], v[156:159], v[0:15]
	ds_read_b64_tr_b16 v[156:157], v252 offset:54784
	ds_read_b64_tr_b16 v[158:159], v252 offset:56832
	v_add_f32_e32 v182, v97, v182
	v_cvt_pk_bf16_f32 v136, v96, v97
	v_exp_f32_e32 v100, v100
	v_exp_f32_e32 v101, v101
	s_waitcnt lgkmcnt(12)
	v_mfma_f32_32x32x16_bf16 v[64:79], v[204:207], v[168:171], v[64:79]
	v_add_f32_e32 v182, v98, v182
	v_add_f32_e32 v182, v99, v182
	v_cvt_pk_bf16_f32 v137, v98, v99
	v_exp_f32_e32 v102, v102
	s_waitcnt lgkmcnt(6)
	v_mfma_f32_32x32x16_bf16 v[48:63], v[132:135], v[144:147], v[48:63]
	ds_read_b64_tr_b16 v[144:145], v252 offset:57344
	ds_read_b64_tr_b16 v[146:147], v252 offset:59392
	v_exp_f32_e32 v103, v103
	v_add_f32_e32 v182, v100, v182
	v_add_f32_e32 v182, v101, v182
	v_cvt_pk_bf16_f32 v138, v100, v101
	v_cvt_pk_bf16_f32 v139, v102, v103
	v_add_f32_e32 v182, v102, v182
	v_mfma_f32_32x32x16_bf16 v[80:95], v[208:211], v[164:167], v[80:95]
	v_add_f32_e32 v182, v103, v182
	v_exp_f32_e32 v104, v104
	v_exp_f32_e32 v105, v105
	v_exp_f32_e32 v106, v106
	s_waitcnt lgkmcnt(6)
	v_mfma_f32_32x32x16_bf16 v[32:47], v[132:135], v[148:151], v[32:47]
	ds_read_b64_tr_b16 v[148:149], v252 offset:57856
	ds_read_b64_tr_b16 v[150:151], v252 offset:59904
	v_exp_f32_e32 v107, v107
	v_add_f32_e32 v182, v104, v182
	v_add_f32_e32 v182, v105, v182
	v_cvt_pk_bf16_f32 v140, v104, v105
	v_mfma_f32_32x32x16_bf16 v[64:79], v[212:215], v[164:167], v[64:79]
	v_exp_f32_e32 v108, v108
	v_exp_f32_e32 v109, v109
	v_add_f32_e32 v182, v106, v182
	v_add_f32_e32 v182, v107, v182
	s_waitcnt lgkmcnt(6)
	v_mfma_f32_32x32x16_bf16 v[16:31], v[132:135], v[152:155], v[16:31]
	ds_read_b64_tr_b16 v[152:153], v252 offset:58368
	ds_read_b64_tr_b16 v[154:155], v252 offset:60416
	v_cvt_pk_bf16_f32 v141, v106, v107
	v_exp_f32_e32 v110, v110
	v_exp_f32_e32 v111, v111
	v_add_f32_e32 v182, v108, v182
	v_mfma_f32_32x32x16_bf16 v[80:95], v[216:219], v[160:163], v[80:95]
	v_add_f32_e32 v182, v109, v182
	v_cvt_pk_bf16_f32 v142, v108, v109
	v_cvt_pk_bf16_f32 v143, v110, v111
	v_add_f32_e32 v182, v110, v182
	v_add_f32_e32 v182, v111, v182
	s_cmp_lt_i32 s55, 0
	s_cselect_b32 s100, -1.0, 1.0
	v_mul_f32_e32 v185, s100, v186
	s_waitcnt lgkmcnt(6)
	v_mfma_f32_32x32x16_bf16 v[0:15], v[132:135], v[156:159], v[0:15]
	ds_read_b64_tr_b16 v[156:157], v252 offset:58880
	ds_read_b64_tr_b16 v[158:159], v252 offset:60928
	v_fma_f32 v187, -v185, v183, s16
	v_fmamk_f32 v112, v185, 0x00000000, v187
	v_fmamk_f32 v113, v185, 0x3f800000, v187
	v_fmamk_f32 v114, v185, 0x40000000, v187
	v_fmamk_f32 v115, v185, 0x40400000, v187
	v_fmamk_f32 v116, v185, 0x41000000, v187
	v_mfma_f32_32x32x16_bf16 v[64:79], v[220:223], v[160:163], v[64:79]
	v_fmamk_f32 v117, v185, 0x41100000, v187
	v_fmamk_f32 v118, v185, 0x41200000, v187
	v_fmamk_f32 v119, v185, 0x41300000, v187
	v_fmamk_f32 v120, v185, 0x41800000, v187
	v_fmamk_f32 v121, v185, 0x41880000, v187
	v_fmamk_f32 v122, v185, 0x41900000, v187
	s_waitcnt lgkmcnt(6)
	v_mfma_f32_32x32x16_bf16 v[48:63], v[136:139], v[144:147], v[48:63]
	ds_read_b64_tr_b16 v[144:145], v252 offset:61440
	ds_read_b64_tr_b16 v[146:147], v252 offset:63488
	v_fmamk_f32 v123, v185, 0x41980000, v187
	v_fmamk_f32 v124, v185, 0x41c00000, v187
	v_fmamk_f32 v125, v185, 0x41c80000, v187
	v_fmamk_f32 v126, v185, 0x41d00000, v187
	v_fmamk_f32 v127, v185, 0x41d80000, v187
	v_fmamk_f32 v96, v185, 0x42000000, v187
	s_waitcnt lgkmcnt(6)
; #define SBAR() __builtin_amdgcn_sched_barrier(0)
; template <int KS> __device__ __forceinline__ void pv_ks(f32x16* o, int vb, bf16x8 pa) {
;     const s16x4 l0 = tr_read<v_rd_off(0, KS, 0)>(vb), h0 = tr_read<v_rd_off(0, KS, 1)>(vb), l1 = tr_read<v_rd_off(1, KS, 0)>(vb), h1 = tr_read<v_rd_off(1, KS, 1)>(vb);
;     const s16x4 l2 = tr_read<v_rd_off(2, KS, 0)>(vb), h2 = tr_read<v_rd_off(2, KS, 1)>(vb), l3 = tr_read<v_rd_off(3, KS, 0)>(vb), h3 = tr_read<v_rd_off(3, KS, 1)>(vb);
;     ...
;     asm volatile("s_waitcnt lgkmcnt(6)" ::: "memory"); SBAR();
;     o[0] = __builtin_amdgcn_mfma_f32_32x32x16_bf16(pa, PK(l0, h0), o[0], 0, 0, 0);
;     asm volatile("s_waitcnt lgkmcnt(4)" ::: "memory"); SBAR();
;     o[1] = __builtin_amdgcn_mfma_f32_32x32x16_bf16(pa, PK(l1, h1), o[1], 0, 0, 0);
;     asm volatile("s_waitcnt lgkmcnt(2)" ::: "memory"); SBAR();
;     o[2] = __builtin_amdgcn_mfma_f32_32x32x16_bf16(pa, PK(l2, h2), o[2], 0, 0, 0);
;     asm volatile("s_waitcnt lgkmcnt(0)" ::: "memory"); SBAR();
;     o[3] = __builtin_amdgcn_mfma_f32_32x32x16_bf16(pa, PK(l3, h3), o[3], 0, 0, 0);
;     ...
; }
; __device__ __forceinline__ void pv_d0(f32x16* o, int vb, bf16x8 pa0, bf16x8 pa1, bf16x8 pa2, bf16x8 pa3) {
;     __builtin_amdgcn_s_setprio(1);
;     pv_ks<0>(o, vb, pa0); pv_ks<1>(o, vb, pa1); pv_ks<2>(o, vb, pa2); pv_ks<3>(o, vb, pa3);
;     __builtin_amdgcn_s_setprio(0);
; }
; __device__ __forceinline__ void exp_half(f32x16& p) {
; #pragma unroll
;     for (int r = 0; r < 16; ++r) p[r] = __builtin_amdgcn_exp2f(p[r]);
; }
; __device__ __forceinline__ void pack_p(const f32x16& p0, const f32x16& p1, float& l_reg, bf16x8& pa0, bf16x8& pa1, bf16x8& pa2, bf16x8& pa3) {
;     float ps = 0;
; #pragma unroll
;     for (int r = 0; r < 16; ++r) ps += p0[r];
; #pragma unroll
;     for (int r = 0; r < 16; ++r) ps += p1[r];
;     l_reg += ps;
;     ...
;     PK4(p0, 0, pa0); PK4(p0, 8, pa1); PK4(p1, 0, pa2); PK4(p1, 8, pa3);
;     ...
; }
; __device__ __forceinline__ void bias_init(f32x16& p0, f32x16& p1, float base, float nslope2, float nM2, int rel  ) {
;     if (rel <= -63 || rel >= 31) {
;         const float sg = (rel < 0) ? -nslope2 : nslope2, lbv = fmaf(-sg, base, nM2);
; #pragma unroll
;         for (int r = 0; r < 16; ++r) { p0[r] = fmaf((float)((r & 3) + 8 * (r >> 2)), sg, lbv); p1[r] = fmaf((float)((r & 3) + 8 * (r >> 2) + 32), sg, lbv); }
;     } else {
; #pragma unroll
	v_mfma_f32_32x32x16_bf16 v[32:47], v[136:139], v[148:151], v[32:47]
	ds_read_b64_tr_b16 v[148:149], v252 offset:61952
	ds_read_b64_tr_b16 v[150:151], v252 offset:64000
	v_fmamk_f32 v97, v185, 0x42040000, v187
	v_fmamk_f32 v98, v185, 0x42080000, v187
	v_fmamk_f32 v99, v185, 0x420c0000, v187
	v_fmamk_f32 v100, v185, 0x42200000, v187
	v_fmamk_f32 v101, v185, 0x42240000, v187
	v_fmamk_f32 v102, v185, 0x42280000, v187
	s_waitcnt lgkmcnt(6)
	v_mfma_f32_32x32x16_bf16 v[16:31], v[136:139], v[152:155], v[16:31]
	ds_read_b64_tr_b16 v[152:153], v252 offset:62464
	ds_read_b64_tr_b16 v[154:155], v252 offset:64512
	v_fmamk_f32 v103, v185, 0x422c0000, v187
	v_fmamk_f32 v104, v185, 0x42400000, v187
	v_fmamk_f32 v105, v185, 0x42440000, v187
	v_fmamk_f32 v106, v185, 0x42480000, v187
	v_fmamk_f32 v107, v185, 0x424c0000, v187
	v_fmamk_f32 v108, v185, 0x42600000, v187
	s_waitcnt lgkmcnt(6)
	v_mfma_f32_32x32x16_bf16 v[0:15], v[136:139], v[156:159], v[0:15]
	ds_read_b64_tr_b16 v[156:157], v252 offset:62976
	ds_read_b64_tr_b16 v[158:159], v252 offset:65024
	v_fmamk_f32 v109, v185, 0x42640000, v187
	v_fmamk_f32 v110, v185, 0x42680000, v187
	v_fmamk_f32 v111, v185, 0x426c0000, v187
	v_exp_f32_e32 v80, v80
	v_exp_f32_e32 v81, v81
	s_waitcnt lgkmcnt(6)
	v_mfma_f32_32x32x16_bf16 v[48:63], v[140:143], v[144:147], v[48:63]
	ds_read_b64_tr_b16 v[144:145], v252 offset:0
	ds_read_b64_tr_b16 v[146:147], v252 offset:2048
	v_exp_f32_e32 v82, v82
	v_exp_f32_e32 v83, v83
	v_add_f32_e32 v182, v80, v182
	v_add_f32_e32 v182, v81, v182
	s_waitcnt lgkmcnt(6)
	v_mfma_f32_32x32x16_bf16 v[32:47], v[140:143], v[148:151], v[32:47]
	ds_read_b64_tr_b16 v[148:149], v252 offset:512
	ds_read_b64_tr_b16 v[150:151], v252 offset:2560
	v_cvt_pk_bf16_f32 v128, v80, v81
	v_exp_f32_e32 v84, v84
	v_exp_f32_e32 v85, v85
	v_add_f32_e32 v182, v82, v182
	s_waitcnt lgkmcnt(6)
	v_mfma_f32_32x32x16_bf16 v[16:31], v[140:143], v[152:155], v[16:31]
	ds_read_b64_tr_b16 v[152:153], v252 offset:1024
	ds_read_b64_tr_b16 v[154:155], v252 offset:3072
	v_add_f32_e32 v182, v83, v182
	v_cvt_pk_bf16_f32 v129, v82, v83
	v_exp_f32_e32 v86, v86
	v_exp_f32_e32 v87, v87
	s_waitcnt lgkmcnt(6)
	v_mfma_f32_32x32x16_bf16 v[0:15], v[140:143], v[156:159], v[0:15]
	ds_read_b64_tr_b16 v[156:157], v252 offset:1536
	ds_read_b64_tr_b16 v[158:159], v252 offset:3584
	v_add_f32_e32 v182, v84, v182
	v_add_f32_e32 v182, v85, v182
	v_cvt_pk_bf16_f32 v130, v84, v85
	v_cvt_pk_bf16_f32 v131, v86, v87
	v_add_f32_e32 v182, v86, v182
	v_add_f32_e32 v182, v87, v182
	s_add_i32 s100, s55, 62
	s_cmp_lt_u32 s100, 93
	s_cbranch_scc0 .Lsym_nodiag_s3
	v_add_f32_e32 v190, 0x00000000, v183
	v_add_f32_e32 v191, 0xc2000000, v183
	v_fma_f32 v112, |v190|, v186, s16
	v_fma_f32 v96, |v191|, v186, s16
	v_add_f32_e32 v190, 0xbf800000, v183
	v_add_f32_e32 v191, 0xc2040000, v183
	v_fma_f32 v113, |v190|, v186, s16
	v_fma_f32 v97, |v191|, v186, s16
	v_add_f32_e32 v190, 0xc0000000, v183
	v_add_f32_e32 v191, 0xc2080000, v183
	v_fma_f32 v114, |v190|, v186, s16
	v_fma_f32 v98, |v191|, v186, s16
	v_add_f32_e32 v190, 0xc0400000, v183
	v_add_f32_e32 v191, 0xc20c0000, v183
	v_fma_f32 v115, |v190|, v186, s16
	v_fma_f32 v99, |v191|, v186, s16
	v_add_f32_e32 v190, 0xc1000000, v183
	v_add_f32_e32 v191, 0xc2200000, v183
	v_fma_f32 v116, |v190|, v186, s16
	v_fma_f32 v100, |v191|, v186, s16
	v_add_f32_e32 v190, 0xc1100000, v183
	v_add_f32_e32 v191, 0xc2240000, v183
	v_fma_f32 v117, |v190|, v186, s16
	v_fma_f32 v101, |v191|, v186, s16
	v_add_f32_e32 v190, 0xc1200000, v183
	v_add_f32_e32 v191, 0xc2280000, v183
	v_fma_f32 v118, |v190|, v186, s16
	v_fma_f32 v102, |v191|, v186, s16
	v_add_f32_e32 v190, 0xc1300000, v183
	v_add_f32_e32 v191, 0xc22c0000, v183
	v_fma_f32 v119, |v190|, v186, s16
	v_fma_f32 v103, |v191|, v186, s16
	v_add_f32_e32 v190, 0xc1800000, v183
	v_add_f32_e32 v191, 0xc2400000, v183
	v_fma_f32 v120, |v190|, v186, s16
	v_fma_f32 v104, |v191|, v186, s16
	v_add_f32_e32 v190, 0xc1880000, v183
	v_add_f32_e32 v191, 0xc2440000, v183
	v_fma_f32 v121, |v190|, v186, s16
	v_fma_f32 v105, |v191|, v186, s16
	v_add_f32_e32 v190, 0xc1900000, v183
	v_add_f32_e32 v191, 0xc2480000, v183
	v_fma_f32 v122, |v190|, v186, s16
	v_fma_f32 v106, |v191|, v186, s16
	v_add_f32_e32 v190, 0xc1980000, v183
	v_add_f32_e32 v191, 0xc24c0000, v183
	v_fma_f32 v123, |v190|, v186, s16
	v_fma_f32 v107, |v191|, v186, s16
	v_add_f32_e32 v190, 0xc1c00000, v183
	v_add_f32_e32 v191, 0xc2600000, v183
	v_fma_f32 v124, |v190|, v186, s16
	v_fma_f32 v108, |v191|, v186, s16
	v_add_f32_e32 v190, 0xc1c80000, v183
	v_add_f32_e32 v191, 0xc2640000, v183
	v_fma_f32 v125, |v190|, v186, s16
	v_fma_f32 v109, |v191|, v186, s16
	v_add_f32_e32 v190, 0xc1d00000, v183
	v_add_f32_e32 v191, 0xc2680000, v183
	v_fma_f32 v126, |v190|, v186, s16
	v_fma_f32 v110, |v191|, v186, s16
	v_add_f32_e32 v190, 0xc1d80000, v183
	v_add_f32_e32 v191, 0xc26c0000, v183
	v_fma_f32 v127, |v190|, v186, s16
	v_fma_f32 v111, |v191|, v186, s16
